# thr histogram step, later passes: prefix test done on the raw float bits (one shift + compare per key); the sortable-key transform only for groups that contain a match
# baseline (speedup 1.0000x reference)
; DI unsigned fkey(float s) {
;   const unsigned u = __float_as_uint(s);
;   return u ^ ((unsigned)((int)u >> 31) | 0x80000000u);
; }
; DI void dsa_thr_item(const Params& p, int b, int qblk, char* smem) {
;     ...
;       } else {
; #pragma unroll
;         for (int i = 0; i < 16; ++i) {
;           unsigned ky = fkey(sc[i]);
;           unsigned hi = (ky >> shift);
;           if ((hi >> 8) == mypref) atomicAdd(&hist[(hi & 255u) * 32 + lr], 1u);
;         }
.Lthr_h_gen:
	s_add_i32 s62, s58, 8
	s_sub_i32 s87, 32, s62
	s_sub_i32 s86, s87, 1
	s_bfm_b32 s87, s87, 0
	s_lshl_b32 s86, 1, s86
	v_and_b32_e32 v154, s86, v94
	v_xor_b32_e32 v155, s86, v94
	v_not_b32_e32 v156, v94
	v_cmp_ne_u32_e64 s[76:77], 0, v154
	v_and_b32_e32 v156, s87, v156
	v_lshrrev_b32_e32 v120, 8, v9
	v_and_b32_e32 v104, 0xff, v9
	v_cndmask_b32_e64 v153, v156, v155, s[76:77]
	v_lshrrev_b32_e32 v121, s62, v22
	v_lshrrev_b32_e32 v122, s62, v21
	v_lshrrev_b32_e32 v123, s62, v20
	v_cmp_eq_u32_e64 s[0:1], v120, v94
	v_cmp_eq_u32_e64 s[6:7], v121, v153
	v_cmp_eq_u32_e64 s[8:9], v122, v153
	v_cmp_eq_u32_e64 s[10:11], v123, v153
	s_or_b64 s[76:77], s[0:1], s[6:7]
	s_or_b64 s[84:85], s[8:9], s[10:11]
	s_or_b64 s[76:77], s[76:77], s[84:85]
	s_cbranch_scc0 .Lthr_g0_skip
	v_ashrrev_i32_e32 v105, 31, v22
	v_ashrrev_i32_e32 v106, 31, v21
	v_ashrrev_i32_e32 v107, 31, v20
	v_bitop3_b32 v105, v105, v22, s67 bitop3:0x36
	v_bitop3_b32 v106, v106, v21, s67 bitop3:0x36
	v_bitop3_b32 v107, v107, v20, s67 bitop3:0x36
	v_bfe_u32 v105, v105, s58, 8
	v_bfe_u32 v106, v106, s58, 8
	v_bfe_u32 v107, v107, s58, 8
	v_lshl_add_u32 v136, v104, 7, v58
	v_lshl_add_u32 v137, v105, 7, v58
	v_lshl_add_u32 v138, v106, 7, v58
	v_lshl_add_u32 v139, v107, 7, v58
	s_and_saveexec_b64 s[74:75], s[0:1]
	ds_add_u32 v136, v71
	s_mov_b64 exec, s[74:75]
	s_and_saveexec_b64 s[74:75], s[6:7]
	ds_add_u32 v137, v71
	s_mov_b64 exec, s[74:75]
	s_and_saveexec_b64 s[74:75], s[8:9]
	ds_add_u32 v138, v71
	s_mov_b64 exec, s[74:75]
	s_and_saveexec_b64 s[74:75], s[10:11]
	ds_add_u32 v139, v71
	s_mov_b64 exec, s[74:75]
.Lthr_g0_skip:
	v_lshrrev_b32_e32 v124, s62, v19
	v_lshrrev_b32_e32 v125, s62, v18
	v_lshrrev_b32_e32 v126, s62, v17
	v_lshrrev_b32_e32 v127, s62, v16
	v_cmp_eq_u32_e64 s[0:1], v124, v153
	v_cmp_eq_u32_e64 s[6:7], v125, v153
	v_cmp_eq_u32_e64 s[8:9], v126, v153
	v_cmp_eq_u32_e64 s[10:11], v127, v153
	s_or_b64 s[76:77], s[0:1], s[6:7]
	s_or_b64 s[84:85], s[8:9], s[10:11]
	s_or_b64 s[76:77], s[76:77], s[84:85]
	s_cbranch_scc0 .Lthr_g1_skip
	v_ashrrev_i32_e32 v108, 31, v19
	v_ashrrev_i32_e32 v109, 31, v18
	v_ashrrev_i32_e32 v110, 31, v17
	v_ashrrev_i32_e32 v111, 31, v16
	v_bitop3_b32 v108, v108, v19, s67 bitop3:0x36
	v_bitop3_b32 v109, v109, v18, s67 bitop3:0x36
	v_bitop3_b32 v110, v110, v17, s67 bitop3:0x36
	v_bitop3_b32 v111, v111, v16, s67 bitop3:0x36
	v_bfe_u32 v108, v108, s58, 8
	v_bfe_u32 v109, v109, s58, 8
	v_bfe_u32 v110, v110, s58, 8
	v_bfe_u32 v111, v111, s58, 8
	v_lshl_add_u32 v140, v108, 7, v58
	v_lshl_add_u32 v141, v109, 7, v58
	v_lshl_add_u32 v142, v110, 7, v58
	v_lshl_add_u32 v143, v111, 7, v58
	s_and_saveexec_b64 s[74:75], s[0:1]
	ds_add_u32 v140, v71
	s_mov_b64 exec, s[74:75]
	s_and_saveexec_b64 s[74:75], s[6:7]
	ds_add_u32 v141, v71
	s_mov_b64 exec, s[74:75]
	s_and_saveexec_b64 s[74:75], s[8:9]
	ds_add_u32 v142, v71
	s_mov_b64 exec, s[74:75]
	s_and_saveexec_b64 s[74:75], s[10:11]
	ds_add_u32 v143, v71
	s_mov_b64 exec, s[74:75]
.Lthr_g1_skip:
	v_lshrrev_b32_e32 v128, s62, v7
	v_lshrrev_b32_e32 v129, s62, v6
	v_lshrrev_b32_e32 v130, s62, v5
	v_lshrrev_b32_e32 v131, s62, v4
	v_cmp_eq_u32_e64 s[0:1], v128, v153
	v_cmp_eq_u32_e64 s[6:7], v129, v153
	v_cmp_eq_u32_e64 s[8:9], v130, v153
	v_cmp_eq_u32_e64 s[10:11], v131, v153
	s_or_b64 s[76:77], s[0:1], s[6:7]
	s_or_b64 s[84:85], s[8:9], s[10:11]
	s_or_b64 s[76:77], s[76:77], s[84:85]
	s_cbranch_scc0 .Lthr_g2_skip
	v_ashrrev_i32_e32 v112, 31, v7
	v_ashrrev_i32_e32 v113, 31, v6
	v_ashrrev_i32_e32 v114, 31, v5
	v_ashrrev_i32_e32 v115, 31, v4
	v_bitop3_b32 v112, v112, v7, s67 bitop3:0x36
	v_bitop3_b32 v113, v113, v6, s67 bitop3:0x36
	v_bitop3_b32 v114, v114, v5, s67 bitop3:0x36
	v_bitop3_b32 v115, v115, v4, s67 bitop3:0x36
	v_bfe_u32 v112, v112, s58, 8
	v_bfe_u32 v113, v113, s58, 8
	v_bfe_u32 v114, v114, s58, 8
	v_bfe_u32 v115, v115, s58, 8
	v_lshl_add_u32 v144, v112, 7, v58
	v_lshl_add_u32 v145, v113, 7, v58
	v_lshl_add_u32 v146, v114, 7, v58
	v_lshl_add_u32 v147, v115, 7, v58
	s_and_saveexec_b64 s[74:75], s[0:1]
	ds_add_u32 v144, v71
	s_mov_b64 exec, s[74:75]
	s_and_saveexec_b64 s[74:75], s[6:7]
	ds_add_u32 v145, v71
	s_mov_b64 exec, s[74:75]
	s_and_saveexec_b64 s[74:75], s[8:9]
	ds_add_u32 v146, v71
	s_mov_b64 exec, s[74:75]
	s_and_saveexec_b64 s[74:75], s[10:11]
	ds_add_u32 v147, v71
	s_mov_b64 exec, s[74:75]
.Lthr_g2_skip:
	v_lshrrev_b32_e32 v132, s62, v3
	v_lshrrev_b32_e32 v133, s62, v2
	v_lshrrev_b32_e32 v134, s62, v1
	v_lshrrev_b32_e32 v135, s62, v0
	v_cmp_eq_u32_e64 s[0:1], v132, v153
	v_cmp_eq_u32_e64 s[6:7], v133, v153
	v_cmp_eq_u32_e64 s[8:9], v134, v153
	v_cmp_eq_u32_e64 s[10:11], v135, v153
	s_or_b64 s[76:77], s[0:1], s[6:7]
	s_or_b64 s[84:85], s[8:9], s[10:11]
	s_or_b64 s[76:77], s[76:77], s[84:85]
	s_cbranch_scc0 .Lthr_g3_skip
	v_ashrrev_i32_e32 v116, 31, v3
	v_ashrrev_i32_e32 v117, 31, v2
	v_ashrrev_i32_e32 v118, 31, v1
	v_ashrrev_i32_e32 v119, 31, v0
	v_bitop3_b32 v116, v116, v3, s67 bitop3:0x36
	v_bitop3_b32 v117, v117, v2, s67 bitop3:0x36
	v_bitop3_b32 v118, v118, v1, s67 bitop3:0x36
	v_bitop3_b32 v119, v119, v0, s67 bitop3:0x36
	v_bfe_u32 v116, v116, s58, 8
	v_bfe_u32 v117, v117, s58, 8
	v_bfe_u32 v118, v118, s58, 8
	v_bfe_u32 v119, v119, s58, 8
	v_lshl_add_u32 v148, v116, 7, v58
	v_lshl_add_u32 v149, v117, 7, v58
	v_lshl_add_u32 v150, v118, 7, v58
	v_lshl_add_u32 v151, v119, 7, v58
	s_and_saveexec_b64 s[74:75], s[0:1]
	ds_add_u32 v148, v71
	s_mov_b64 exec, s[74:75]
	s_and_saveexec_b64 s[74:75], s[6:7]
	ds_add_u32 v149, v71
	s_mov_b64 exec, s[74:75]
	s_and_saveexec_b64 s[74:75], s[8:9]
	ds_add_u32 v150, v71
	s_mov_b64 exec, s[74:75]
	s_and_saveexec_b64 s[74:75], s[10:11]
	ds_add_u32 v151, v71
	s_mov_b64 exec, s[74:75]
